# FSsmY epilogue rebuilt by hand: 8-wide batched gelu stages per store group, saddr-form stores with SALU-stepped base (address VALU 54 -> 7 per half)
# baseline (speedup 1.0000x reference)
; #define GAS __attribute__((address_space(1)))
; __device__ __forceinline__ float fexp2(float x) { return __builtin_amdgcn_exp2f(x); }
; __device__ __forceinline__ float frcp(float x) { return __builtin_amdgcn_rcpf(x); }
; __device__ __forceinline__ float gelu_tanh(float x) { const float u = 0.7978845608028654f * (x + 0.044715f * x * x * x); return x * sigmoidf_(2.f * u); }
; __device__ __forceinline__ u32x4 pack8(f32x4 a, f32x4 b) { u32x4 w; w.x = pk2(a[0], a[1]); w.y = pk2(a[2], a[3]); w.z = pk2(b[0], b[1]); w.w = pk2(b[2], b[3]); return w; }
; __device__ __forceinline__ float sigmoidf_(float x) { return frcp(1.f + fexp2(-x * LOG2E)); }
; __device__ __forceinline__ float siluf_(float x) { return x * sigmoidf_(x); }
;     __device__ __forceinline__ void operator()(const Unit& u, int row, int col, f32x4 v0, f32x4 v1) const {
;         const int g = row >> 11, rowg = row & 2047, j = col >> 4, p = col & 15;
; #pragma unroll
;         for (int i = 0; i < 4; ++i) { v0[i] = gelu_tanh(v0[i]); v1[i] = gelu_tanh(v1[i]); }
;         *(GAS u32x4*)(Y + ((size_t)(rowg * 16 + j) * 512 + g * 16 + p)) = pack8(v0, v1);
.LBB0_699:
	s_lshl_b32 s52, s72, 8
	s_add_i32 s52, s52, s85
	v_or_b32_e32 v153, s52, v146
	v_lshlrev_b32_e32 v153, 4, v153
	v_and_b32_e32 v153, 0x7cf0, v153
	s_ashr_i32 s21, s52, 7
	s_and_b32 s50, s21, -16
	s_ashr_i32 s51, s50, 31
	s_lshl_b64 s[50:51], s[50:51], 1
	s_add_u32 s50, s50, s36
	s_addc_u32 s51, s51, s37
	v_add_u32_e32 v162, v153, v148
	v_add_u32_e32 v153, v153, v149
	v_lshl_add_u32 v162, v162, 10, v136
	v_lshl_add_u32 v153, v153, 10, v136
	v_mul_f32_e32 v154, 0xbdd2d3e8, v120
	v_mul_f32_e32 v155, 0xbdd2d3e8, v121
	v_mul_f32_e32 v156, 0xbdd2d3e8, v122
	v_mul_f32_e32 v157, 0xbdd2d3e8, v123
	v_mul_f32_e32 v158, 0xbdd2d3e8, v124
	v_mul_f32_e32 v159, 0xbdd2d3e8, v125
	v_mul_f32_e32 v160, 0xbdd2d3e8, v126
	v_mul_f32_e32 v161, 0xbdd2d3e8, v127
	v_fmaak_f32 v154, v120, v154, 0xc0135761
	v_fmaak_f32 v155, v121, v155, 0xc0135761
	v_fmaak_f32 v156, v122, v156, 0xc0135761
	v_fmaak_f32 v157, v123, v157, 0xc0135761
	v_fmaak_f32 v158, v124, v158, 0xc0135761
	v_fmaak_f32 v159, v125, v159, 0xc0135761
	v_fmaak_f32 v160, v126, v160, 0xc0135761
	v_fmaak_f32 v161, v127, v161, 0xc0135761
	v_mul_f32_e32 v154, v120, v154
	v_mul_f32_e32 v155, v121, v155
	v_mul_f32_e32 v156, v122, v156
	v_mul_f32_e32 v157, v123, v157
	v_mul_f32_e32 v158, v124, v158
	v_mul_f32_e32 v159, v125, v159
	v_mul_f32_e32 v160, v126, v160
	v_mul_f32_e32 v161, v127, v161
	v_exp_f32_e32 v154, v154
	v_exp_f32_e32 v155, v155
	v_exp_f32_e32 v156, v156
	v_exp_f32_e32 v157, v157
	v_exp_f32_e32 v158, v158
	v_exp_f32_e32 v159, v159
	v_exp_f32_e32 v160, v160
	v_exp_f32_e32 v161, v161
	v_add_f32_e32 v154, 1.0, v154
	v_add_f32_e32 v155, 1.0, v155
	v_add_f32_e32 v156, 1.0, v156
	v_add_f32_e32 v157, 1.0, v157
	v_add_f32_e32 v158, 1.0, v158
	v_add_f32_e32 v159, 1.0, v159
	v_add_f32_e32 v160, 1.0, v160
	v_add_f32_e32 v161, 1.0, v161
	v_rcp_f32_e32 v154, v154
	v_rcp_f32_e32 v155, v155
	v_rcp_f32_e32 v156, v156
	v_rcp_f32_e32 v157, v157
	v_rcp_f32_e32 v158, v158
	v_rcp_f32_e32 v159, v159
	v_rcp_f32_e32 v160, v160
	v_rcp_f32_e32 v161, v161
	v_pk_mul_f32 v[154:155], v[120:121], v[154:155]
	v_pk_mul_f32 v[156:157], v[122:123], v[156:157]
	v_pk_mul_f32 v[158:159], v[124:125], v[158:159]
	v_pk_mul_f32 v[160:161], v[126:127], v[160:161]
	v_cvt_pk_bf16_f32 v120, v158, v159
	v_cvt_pk_bf16_f32 v121, v160, v161
	v_cvt_pk_bf16_f32 v122, v154, v155
	v_cvt_pk_bf16_f32 v123, v156, v157
	global_store_dwordx4 v162, v[120:123], s[50:51]
	v_mul_f32_e32 v154, 0xbdd2d3e8, v112
	v_mul_f32_e32 v155, 0xbdd2d3e8, v113
	v_mul_f32_e32 v156, 0xbdd2d3e8, v114
	v_mul_f32_e32 v157, 0xbdd2d3e8, v115
	v_mul_f32_e32 v158, 0xbdd2d3e8, v116
	v_mul_f32_e32 v159, 0xbdd2d3e8, v117
	v_mul_f32_e32 v160, 0xbdd2d3e8, v118
	v_mul_f32_e32 v161, 0xbdd2d3e8, v119
	v_fmaak_f32 v154, v112, v154, 0xc0135761
	v_fmaak_f32 v155, v113, v155, 0xc0135761
	v_fmaak_f32 v156, v114, v156, 0xc0135761
	v_fmaak_f32 v157, v115, v157, 0xc0135761
	v_fmaak_f32 v158, v116, v158, 0xc0135761
	v_fmaak_f32 v159, v117, v159, 0xc0135761
	v_fmaak_f32 v160, v118, v160, 0xc0135761
	v_fmaak_f32 v161, v119, v161, 0xc0135761
	v_mul_f32_e32 v154, v112, v154
	v_mul_f32_e32 v155, v113, v155
	v_mul_f32_e32 v156, v114, v156
	v_mul_f32_e32 v157, v115, v157
	v_mul_f32_e32 v158, v116, v158
	v_mul_f32_e32 v159, v117, v159
	v_mul_f32_e32 v160, v118, v160
	v_mul_f32_e32 v161, v119, v161
	v_exp_f32_e32 v154, v154
	v_exp_f32_e32 v155, v155
	v_exp_f32_e32 v156, v156
	v_exp_f32_e32 v157, v157
	v_exp_f32_e32 v158, v158
	v_exp_f32_e32 v159, v159
	v_exp_f32_e32 v160, v160
	v_exp_f32_e32 v161, v161
	v_add_f32_e32 v154, 1.0, v154
	v_add_f32_e32 v155, 1.0, v155
	v_add_f32_e32 v156, 1.0, v156
	v_add_f32_e32 v157, 1.0, v157
	v_add_f32_e32 v158, 1.0, v158
	v_add_f32_e32 v159, 1.0, v159
	v_add_f32_e32 v160, 1.0, v160
	v_add_f32_e32 v161, 1.0, v161
	v_rcp_f32_e32 v154, v154
	v_rcp_f32_e32 v155, v155
	v_rcp_f32_e32 v156, v156
	v_rcp_f32_e32 v157, v157
	v_rcp_f32_e32 v158, v158
	v_rcp_f32_e32 v159, v159
	v_rcp_f32_e32 v160, v160
	v_rcp_f32_e32 v161, v161
	v_pk_mul_f32 v[154:155], v[112:113], v[154:155]
	v_pk_mul_f32 v[156:157], v[114:115], v[156:157]
	v_pk_mul_f32 v[158:159], v[116:117], v[158:159]
	v_pk_mul_f32 v[160:161], v[118:119], v[160:161]
	v_cvt_pk_bf16_f32 v112, v158, v159
	v_cvt_pk_bf16_f32 v113, v160, v161
	v_cvt_pk_bf16_f32 v114, v154, v155
	v_cvt_pk_bf16_f32 v115, v156, v157
	global_store_dwordx4 v153, v[112:115], s[50:51]
	s_add_u32 s50, s50, 0x40000
	s_addc_u32 s51, s51, 0
	v_mul_f32_e32 v154, 0xbdd2d3e8, v104
	v_mul_f32_e32 v155, 0xbdd2d3e8, v105
	v_mul_f32_e32 v156, 0xbdd2d3e8, v106
	v_mul_f32_e32 v157, 0xbdd2d3e8, v107
	v_mul_f32_e32 v158, 0xbdd2d3e8, v108
	v_mul_f32_e32 v159, 0xbdd2d3e8, v109
	v_mul_f32_e32 v160, 0xbdd2d3e8, v110
	v_mul_f32_e32 v161, 0xbdd2d3e8, v111
	v_fmaak_f32 v154, v104, v154, 0xc0135761
	v_fmaak_f32 v155, v105, v155, 0xc0135761
	v_fmaak_f32 v156, v106, v156, 0xc0135761
	v_fmaak_f32 v157, v107, v157, 0xc0135761
	v_fmaak_f32 v158, v108, v158, 0xc0135761
	v_fmaak_f32 v159, v109, v159, 0xc0135761
	v_fmaak_f32 v160, v110, v160, 0xc0135761
	v_fmaak_f32 v161, v111, v161, 0xc0135761
	v_mul_f32_e32 v154, v104, v154
	v_mul_f32_e32 v155, v105, v155
	v_mul_f32_e32 v156, v106, v156
	v_mul_f32_e32 v157, v107, v157
	v_mul_f32_e32 v158, v108, v158
	v_mul_f32_e32 v159, v109, v159
	v_mul_f32_e32 v160, v110, v160
	v_mul_f32_e32 v161, v111, v161
	v_exp_f32_e32 v154, v154
	v_exp_f32_e32 v155, v155
	v_exp_f32_e32 v156, v156
	v_exp_f32_e32 v157, v157
	v_exp_f32_e32 v158, v158
	v_exp_f32_e32 v159, v159
	v_exp_f32_e32 v160, v160
	v_exp_f32_e32 v161, v161
	v_add_f32_e32 v154, 1.0, v154
	v_add_f32_e32 v155, 1.0, v155
	v_add_f32_e32 v156, 1.0, v156
	v_add_f32_e32 v157, 1.0, v157
; #define GAS __attribute__((address_space(1)))
; __device__ __forceinline__ float fexp2(float x) { return __builtin_amdgcn_exp2f(x); }
; __device__ __forceinline__ float frcp(float x) { return __builtin_amdgcn_rcpf(x); }
; __device__ __forceinline__ float gelu_tanh(float x) { const float u = 0.7978845608028654f * (x + 0.044715f * x * x * x); return x * sigmoidf_(2.f * u); }
; __device__ __forceinline__ u32x4 pack8(f32x4 a, f32x4 b) { u32x4 w; w.x = pk2(a[0], a[1]); w.y = pk2(a[2], a[3]); w.z = pk2(b[0], b[1]); w.w = pk2(b[2], b[3]); return w; }
; __device__ __forceinline__ float sigmoidf_(float x) { return frcp(1.f + fexp2(-x * LOG2E)); }
; __device__ __forceinline__ float siluf_(float x) { return x * sigmoidf_(x); }
;     __device__ __forceinline__ void operator()(const Unit& u, int row, int col, f32x4 v0, f32x4 v1) const {
;         const int g = row >> 11, rowg = row & 2047, j = col >> 4, p = col & 15;
; #pragma unroll
;         for (int i = 0; i < 4; ++i) { v0[i] = gelu_tanh(v0[i]); v1[i] = gelu_tanh(v1[i]); }
;         *(GAS u32x4*)(Y + ((size_t)(rowg * 16 + j) * 512 + g * 16 + p)) = pack8(v0, v1);
	v_add_f32_e32 v158, 1.0, v158
	v_add_f32_e32 v159, 1.0, v159
	v_add_f32_e32 v160, 1.0, v160
	v_add_f32_e32 v161, 1.0, v161
	v_rcp_f32_e32 v154, v154
	v_rcp_f32_e32 v155, v155
	v_rcp_f32_e32 v156, v156
	v_rcp_f32_e32 v157, v157
	v_rcp_f32_e32 v158, v158
	v_rcp_f32_e32 v159, v159
	v_rcp_f32_e32 v160, v160
	v_rcp_f32_e32 v161, v161
	v_pk_mul_f32 v[154:155], v[104:105], v[154:155]
	v_pk_mul_f32 v[156:157], v[106:107], v[156:157]
	v_pk_mul_f32 v[158:159], v[108:109], v[158:159]
	v_pk_mul_f32 v[160:161], v[110:111], v[160:161]
	v_cvt_pk_bf16_f32 v104, v158, v159
	v_cvt_pk_bf16_f32 v105, v160, v161
	v_cvt_pk_bf16_f32 v106, v154, v155
	v_cvt_pk_bf16_f32 v107, v156, v157
	global_store_dwordx4 v162, v[104:107], s[50:51]
	v_mul_f32_e32 v154, 0xbdd2d3e8, v96
	v_mul_f32_e32 v155, 0xbdd2d3e8, v97
	v_mul_f32_e32 v156, 0xbdd2d3e8, v98
	v_mul_f32_e32 v157, 0xbdd2d3e8, v99
	v_mul_f32_e32 v158, 0xbdd2d3e8, v100
	v_mul_f32_e32 v159, 0xbdd2d3e8, v101
	v_mul_f32_e32 v160, 0xbdd2d3e8, v102
	v_mul_f32_e32 v161, 0xbdd2d3e8, v103
	v_fmaak_f32 v154, v96, v154, 0xc0135761
	v_fmaak_f32 v155, v97, v155, 0xc0135761
	v_fmaak_f32 v156, v98, v156, 0xc0135761
	v_fmaak_f32 v157, v99, v157, 0xc0135761
	v_fmaak_f32 v158, v100, v158, 0xc0135761
	v_fmaak_f32 v159, v101, v159, 0xc0135761
	v_fmaak_f32 v160, v102, v160, 0xc0135761
	v_fmaak_f32 v161, v103, v161, 0xc0135761
	v_mul_f32_e32 v154, v96, v154
	v_mul_f32_e32 v155, v97, v155
	v_mul_f32_e32 v156, v98, v156
	v_mul_f32_e32 v157, v99, v157
	v_mul_f32_e32 v158, v100, v158
	v_mul_f32_e32 v159, v101, v159
	v_mul_f32_e32 v160, v102, v160
	v_mul_f32_e32 v161, v103, v161
	v_exp_f32_e32 v154, v154
	v_exp_f32_e32 v155, v155
	v_exp_f32_e32 v156, v156
	v_exp_f32_e32 v157, v157
	v_exp_f32_e32 v158, v158
	v_exp_f32_e32 v159, v159
	v_exp_f32_e32 v160, v160
	v_exp_f32_e32 v161, v161
	v_add_f32_e32 v154, 1.0, v154
	v_add_f32_e32 v155, 1.0, v155
	v_add_f32_e32 v156, 1.0, v156
	v_add_f32_e32 v157, 1.0, v157
	v_add_f32_e32 v158, 1.0, v158
	v_add_f32_e32 v159, 1.0, v159
	v_add_f32_e32 v160, 1.0, v160
	v_add_f32_e32 v161, 1.0, v161
	v_rcp_f32_e32 v154, v154
	v_rcp_f32_e32 v155, v155
	v_rcp_f32_e32 v156, v156
	v_rcp_f32_e32 v157, v157
	v_rcp_f32_e32 v158, v158
	v_rcp_f32_e32 v159, v159
	v_rcp_f32_e32 v160, v160
	v_rcp_f32_e32 v161, v161
	v_pk_mul_f32 v[154:155], v[96:97], v[154:155]
	v_pk_mul_f32 v[156:157], v[98:99], v[156:157]
	v_pk_mul_f32 v[158:159], v[100:101], v[158:159]
	v_pk_mul_f32 v[160:161], v[102:103], v[160:161]
	v_cvt_pk_bf16_f32 v96, v158, v159
	v_cvt_pk_bf16_f32 v97, v160, v161
	v_cvt_pk_bf16_f32 v98, v154, v155
	v_cvt_pk_bf16_f32 v99, v156, v157
	global_store_dwordx4 v153, v[96:99], s[50:51]
	s_add_u32 s50, s50, 0x40000
	s_addc_u32 s51, s51, 0
	v_mul_f32_e32 v154, 0xbdd2d3e8, v88
	v_mul_f32_e32 v155, 0xbdd2d3e8, v89
	v_mul_f32_e32 v156, 0xbdd2d3e8, v90
	v_mul_f32_e32 v157, 0xbdd2d3e8, v91
	v_mul_f32_e32 v158, 0xbdd2d3e8, v92
	v_mul_f32_e32 v159, 0xbdd2d3e8, v93
	v_mul_f32_e32 v160, 0xbdd2d3e8, v94
	v_mul_f32_e32 v161, 0xbdd2d3e8, v95
	v_fmaak_f32 v154, v88, v154, 0xc0135761
	v_fmaak_f32 v155, v89, v155, 0xc0135761
	v_fmaak_f32 v156, v90, v156, 0xc0135761
	v_fmaak_f32 v157, v91, v157, 0xc0135761
	v_fmaak_f32 v158, v92, v158, 0xc0135761
	v_fmaak_f32 v159, v93, v159, 0xc0135761
	v_fmaak_f32 v160, v94, v160, 0xc0135761
	v_fmaak_f32 v161, v95, v161, 0xc0135761
	v_mul_f32_e32 v154, v88, v154
	v_mul_f32_e32 v155, v89, v155
	v_mul_f32_e32 v156, v90, v156
	v_mul_f32_e32 v157, v91, v157
	v_mul_f32_e32 v158, v92, v158
	v_mul_f32_e32 v159, v93, v159
	v_mul_f32_e32 v160, v94, v160
	v_mul_f32_e32 v161, v95, v161
	v_exp_f32_e32 v154, v154
	v_exp_f32_e32 v155, v155
	v_exp_f32_e32 v156, v156
	v_exp_f32_e32 v157, v157
	v_exp_f32_e32 v158, v158
	v_exp_f32_e32 v159, v159
	v_exp_f32_e32 v160, v160
	v_exp_f32_e32 v161, v161
	v_add_f32_e32 v154, 1.0, v154
	v_add_f32_e32 v155, 1.0, v155
	v_add_f32_e32 v156, 1.0, v156
	v_add_f32_e32 v157, 1.0, v157
	v_add_f32_e32 v158, 1.0, v158
	v_add_f32_e32 v159, 1.0, v159
	v_add_f32_e32 v160, 1.0, v160
	v_add_f32_e32 v161, 1.0, v161
	v_rcp_f32_e32 v154, v154
	v_rcp_f32_e32 v155, v155
	v_rcp_f32_e32 v156, v156
	v_rcp_f32_e32 v157, v157
	v_rcp_f32_e32 v158, v158
	v_rcp_f32_e32 v159, v159
	v_rcp_f32_e32 v160, v160
	v_rcp_f32_e32 v161, v161
	v_pk_mul_f32 v[154:155], v[88:89], v[154:155]
	v_pk_mul_f32 v[156:157], v[90:91], v[156:157]
	v_pk_mul_f32 v[158:159], v[92:93], v[158:159]
	v_pk_mul_f32 v[160:161], v[94:95], v[160:161]
	v_cvt_pk_bf16_f32 v88, v158, v159
	v_cvt_pk_bf16_f32 v89, v160, v161
	v_cvt_pk_bf16_f32 v90, v154, v155
	v_cvt_pk_bf16_f32 v91, v156, v157
	global_store_dwordx4 v162, v[88:91], s[50:51]
	v_mul_f32_e32 v154, 0xbdd2d3e8, v80
	v_mul_f32_e32 v155, 0xbdd2d3e8, v81
	v_mul_f32_e32 v156, 0xbdd2d3e8, v82
	v_mul_f32_e32 v157, 0xbdd2d3e8, v83
	v_mul_f32_e32 v158, 0xbdd2d3e8, v84
	v_mul_f32_e32 v159, 0xbdd2d3e8, v85
	v_mul_f32_e32 v160, 0xbdd2d3e8, v86
	v_mul_f32_e32 v161, 0xbdd2d3e8, v87
	v_fmaak_f32 v154, v80, v154, 0xc0135761
	v_fmaak_f32 v155, v81, v155, 0xc0135761
	v_fmaak_f32 v156, v82, v156, 0xc0135761
	v_fmaak_f32 v157, v83, v157, 0xc0135761
	v_fmaak_f32 v158, v84, v158, 0xc0135761
	v_fmaak_f32 v159, v85, v159, 0xc0135761
	v_fmaak_f32 v160, v86, v160, 0xc0135761
	v_fmaak_f32 v161, v87, v161, 0xc0135761
	v_mul_f32_e32 v154, v80, v154
	v_mul_f32_e32 v155, v81, v155
	v_mul_f32_e32 v156, v82, v156
	v_mul_f32_e32 v157, v83, v157
	v_mul_f32_e32 v158, v84, v158
	v_mul_f32_e32 v159, v85, v159
	v_mul_f32_e32 v160, v86, v160
	v_mul_f32_e32 v161, v87, v161
	v_exp_f32_e32 v154, v154
	v_exp_f32_e32 v155, v155
	v_exp_f32_e32 v156, v156
	v_exp_f32_e32 v157, v157
	v_exp_f32_e32 v158, v158
	v_exp_f32_e32 v159, v159
; #define GAS __attribute__((address_space(1)))
; __device__ __forceinline__ float gelu_tanh(float x) { const float u = 0.7978845608028654f * (x + 0.044715f * x * x * x); return x * sigmoidf_(2.f * u); }
; __device__ __forceinline__ u32x4 pack8(f32x4 a, f32x4 b) { u32x4 w; w.x = pk2(a[0], a[1]); w.y = pk2(a[2], a[3]); w.z = pk2(b[0], b[1]); w.w = pk2(b[2], b[3]); return w; }
;     __device__ __forceinline__ void operator()(const f32x4 (&acc)[2][2][4][2], const Unit& u, int wr, int wc, int fr, int fq) const {
;     ...
; #pragma unroll
;             for (int m = 0; m < 4; ++m) {
;                 const int row = u.pm * BM + ai * HALF + wr * 64 + m * 16 + fr;
; #pragma unroll
;                 for (int bj = 0; bj < 2; ++bj) f(u, row, bj * HALF + wc * 32 + 8 * fq, acc[ai][bj][m][0], acc[ai][bj][m][1]);
;             }
;     __device__ __forceinline__ void operator()(const Unit& u, int row, int col, f32x4 v0, f32x4 v1) const {
;         const int g = row >> 11, rowg = row & 2047, j = col >> 4, p = col & 15;
; #pragma unroll
;         for (int i = 0; i < 4; ++i) { v0[i] = gelu_tanh(v0[i]); v1[i] = gelu_tanh(v1[i]); }
;         *(GAS u32x4*)(Y + ((size_t)(rowg * 16 + j) * 512 + g * 16 + p)) = pack8(v0, v1);
	v_exp_f32_e32 v160, v160
	v_exp_f32_e32 v161, v161
	v_add_f32_e32 v154, 1.0, v154
	v_add_f32_e32 v155, 1.0, v155
	v_add_f32_e32 v156, 1.0, v156
	v_add_f32_e32 v157, 1.0, v157
	v_add_f32_e32 v158, 1.0, v158
	v_add_f32_e32 v159, 1.0, v159
	v_add_f32_e32 v160, 1.0, v160
	v_add_f32_e32 v161, 1.0, v161
	v_rcp_f32_e32 v154, v154
	v_rcp_f32_e32 v155, v155
	v_rcp_f32_e32 v156, v156
	v_rcp_f32_e32 v157, v157
	v_rcp_f32_e32 v158, v158
	v_rcp_f32_e32 v159, v159
	v_rcp_f32_e32 v160, v160
	v_rcp_f32_e32 v161, v161
	v_pk_mul_f32 v[154:155], v[80:81], v[154:155]
	v_pk_mul_f32 v[156:157], v[82:83], v[156:157]
	v_pk_mul_f32 v[158:159], v[84:85], v[158:159]
	v_pk_mul_f32 v[160:161], v[86:87], v[160:161]
	v_cvt_pk_bf16_f32 v80, v158, v159
	v_cvt_pk_bf16_f32 v81, v160, v161
	v_cvt_pk_bf16_f32 v82, v154, v155
	v_cvt_pk_bf16_f32 v83, v156, v157
	global_store_dwordx4 v153, v[80:83], s[50:51]
	s_add_u32 s50, s50, 0x40000
	s_addc_u32 s51, s51, 0
	v_mul_f32_e32 v154, 0xbdd2d3e8, v72
	v_mul_f32_e32 v155, 0xbdd2d3e8, v73
	v_mul_f32_e32 v156, 0xbdd2d3e8, v74
	v_mul_f32_e32 v157, 0xbdd2d3e8, v75
	v_mul_f32_e32 v158, 0xbdd2d3e8, v76
	v_mul_f32_e32 v159, 0xbdd2d3e8, v77
	v_mul_f32_e32 v160, 0xbdd2d3e8, v78
	v_mul_f32_e32 v161, 0xbdd2d3e8, v79
	v_fmaak_f32 v154, v72, v154, 0xc0135761
	v_fmaak_f32 v155, v73, v155, 0xc0135761
	v_fmaak_f32 v156, v74, v156, 0xc0135761
	v_fmaak_f32 v157, v75, v157, 0xc0135761
	v_fmaak_f32 v158, v76, v158, 0xc0135761
	v_fmaak_f32 v159, v77, v159, 0xc0135761
	v_fmaak_f32 v160, v78, v160, 0xc0135761
	v_fmaak_f32 v161, v79, v161, 0xc0135761
	v_mul_f32_e32 v154, v72, v154
	v_mul_f32_e32 v155, v73, v155
	v_mul_f32_e32 v156, v74, v156
	v_mul_f32_e32 v157, v75, v157
	v_mul_f32_e32 v158, v76, v158
	v_mul_f32_e32 v159, v77, v159
	v_mul_f32_e32 v160, v78, v160
	v_mul_f32_e32 v161, v79, v161
	v_exp_f32_e32 v154, v154
	v_exp_f32_e32 v155, v155
	v_exp_f32_e32 v156, v156
	v_exp_f32_e32 v157, v157
	v_exp_f32_e32 v158, v158
	v_exp_f32_e32 v159, v159
	v_exp_f32_e32 v160, v160
	v_exp_f32_e32 v161, v161
	v_add_f32_e32 v154, 1.0, v154
	v_add_f32_e32 v155, 1.0, v155
	v_add_f32_e32 v156, 1.0, v156
	v_add_f32_e32 v157, 1.0, v157
	v_add_f32_e32 v158, 1.0, v158
	v_add_f32_e32 v159, 1.0, v159
	v_add_f32_e32 v160, 1.0, v160
	v_add_f32_e32 v161, 1.0, v161
	v_rcp_f32_e32 v154, v154
	v_rcp_f32_e32 v155, v155
	v_rcp_f32_e32 v156, v156
	v_rcp_f32_e32 v157, v157
	v_rcp_f32_e32 v158, v158
	v_rcp_f32_e32 v159, v159
	v_rcp_f32_e32 v160, v160
	v_rcp_f32_e32 v161, v161
	v_pk_mul_f32 v[154:155], v[72:73], v[154:155]
	v_pk_mul_f32 v[156:157], v[74:75], v[156:157]
	v_pk_mul_f32 v[158:159], v[76:77], v[158:159]
	v_pk_mul_f32 v[160:161], v[78:79], v[160:161]
	v_cvt_pk_bf16_f32 v72, v158, v159
	v_cvt_pk_bf16_f32 v73, v160, v161
	v_cvt_pk_bf16_f32 v74, v154, v155
	v_cvt_pk_bf16_f32 v75, v156, v157
	global_store_dwordx4 v162, v[72:75], s[50:51]
	v_mul_f32_e32 v154, 0xbdd2d3e8, v64
	v_mul_f32_e32 v155, 0xbdd2d3e8, v65
	v_mul_f32_e32 v156, 0xbdd2d3e8, v66
	v_mul_f32_e32 v157, 0xbdd2d3e8, v67
	v_mul_f32_e32 v158, 0xbdd2d3e8, v68
	v_mul_f32_e32 v159, 0xbdd2d3e8, v69
	v_mul_f32_e32 v160, 0xbdd2d3e8, v70
	v_mul_f32_e32 v161, 0xbdd2d3e8, v71
	v_fmaak_f32 v154, v64, v154, 0xc0135761
	v_fmaak_f32 v155, v65, v155, 0xc0135761
	v_fmaak_f32 v156, v66, v156, 0xc0135761
	v_fmaak_f32 v157, v67, v157, 0xc0135761
	v_fmaak_f32 v158, v68, v158, 0xc0135761
	v_fmaak_f32 v159, v69, v159, 0xc0135761
	v_fmaak_f32 v160, v70, v160, 0xc0135761
	v_fmaak_f32 v161, v71, v161, 0xc0135761
	v_mul_f32_e32 v154, v64, v154
	v_mul_f32_e32 v155, v65, v155
	v_mul_f32_e32 v156, v66, v156
	v_mul_f32_e32 v157, v67, v157
	v_mul_f32_e32 v158, v68, v158
	v_mul_f32_e32 v159, v69, v159
	v_mul_f32_e32 v160, v70, v160
	v_mul_f32_e32 v161, v71, v161
	v_exp_f32_e32 v154, v154
	v_exp_f32_e32 v155, v155
	v_exp_f32_e32 v156, v156
	v_exp_f32_e32 v157, v157
	v_exp_f32_e32 v158, v158
	v_exp_f32_e32 v159, v159
	v_exp_f32_e32 v160, v160
	v_exp_f32_e32 v161, v161
	v_add_f32_e32 v154, 1.0, v154
	v_add_f32_e32 v155, 1.0, v155
	v_add_f32_e32 v156, 1.0, v156
	v_add_f32_e32 v157, 1.0, v157
	v_add_f32_e32 v158, 1.0, v158
	v_add_f32_e32 v159, 1.0, v159
	v_add_f32_e32 v160, 1.0, v160
	v_add_f32_e32 v161, 1.0, v161
	v_rcp_f32_e32 v154, v154
	v_rcp_f32_e32 v155, v155
	v_rcp_f32_e32 v156, v156
	v_rcp_f32_e32 v157, v157
	v_rcp_f32_e32 v158, v158
	v_rcp_f32_e32 v159, v159
	v_rcp_f32_e32 v160, v160
	v_rcp_f32_e32 v161, v161
	v_pk_mul_f32 v[154:155], v[64:65], v[154:155]
	v_pk_mul_f32 v[156:157], v[66:67], v[156:157]
	v_pk_mul_f32 v[158:159], v[68:69], v[158:159]
	v_pk_mul_f32 v[160:161], v[70:71], v[160:161]
	v_cvt_pk_bf16_f32 v64, v158, v159
	v_cvt_pk_bf16_f32 v65, v160, v161
	v_cvt_pk_bf16_f32 v66, v154, v155
	v_cvt_pk_bf16_f32 v67, v156, v157
	global_store_dwordx4 v153, v[64:67], s[50:51]
	s_addk_i32 s52, 0x80
	v_or_b32_e32 v153, s52, v146
	v_lshlrev_b32_e32 v153, 4, v153
	v_and_b32_e32 v153, 0x7cf0, v153
	s_ashr_i32 s21, s52, 7
	s_and_b32 s50, s21, -16
	s_ashr_i32 s51, s50, 31
	s_lshl_b64 s[50:51], s[50:51], 1
	s_add_u32 s50, s50, s36
	s_addc_u32 s51, s51, s37
	v_add_u32_e32 v162, v153, v148
	v_add_u32_e32 v153, v153, v149
	v_lshl_add_u32 v162, v162, 10, v136
	v_lshl_add_u32 v153, v153, 10, v136
	v_mul_f32_e32 v154, 0xbdd2d3e8, v56
	v_mul_f32_e32 v155, 0xbdd2d3e8, v57
	v_mul_f32_e32 v156, 0xbdd2d3e8, v58
	v_mul_f32_e32 v157, 0xbdd2d3e8, v59
	v_mul_f32_e32 v158, 0xbdd2d3e8, v60
	v_mul_f32_e32 v159, 0xbdd2d3e8, v61
	v_mul_f32_e32 v160, 0xbdd2d3e8, v62
	v_mul_f32_e32 v161, 0xbdd2d3e8, v63
	v_fmaak_f32 v154, v56, v154, 0xc0135761
	v_fmaak_f32 v155, v57, v155, 0xc0135761
	v_fmaak_f32 v156, v58, v156, 0xc0135761
	v_fmaak_f32 v157, v59, v157, 0xc0135761
; #define GAS __attribute__((address_space(1)))
; __device__ __forceinline__ float fexp2(float x) { return __builtin_amdgcn_exp2f(x); }
; __device__ __forceinline__ float frcp(float x) { return __builtin_amdgcn_rcpf(x); }
; __device__ __forceinline__ float gelu_tanh(float x) { const float u = 0.7978845608028654f * (x + 0.044715f * x * x * x); return x * sigmoidf_(2.f * u); }
; __device__ __forceinline__ u32x4 pack8(f32x4 a, f32x4 b) { u32x4 w; w.x = pk2(a[0], a[1]); w.y = pk2(a[2], a[3]); w.z = pk2(b[0], b[1]); w.w = pk2(b[2], b[3]); return w; }
; __device__ __forceinline__ float sigmoidf_(float x) { return frcp(1.f + fexp2(-x * LOG2E)); }
; __device__ __forceinline__ float siluf_(float x) { return x * sigmoidf_(x); }
;     __device__ __forceinline__ void operator()(const Unit& u, int row, int col, f32x4 v0, f32x4 v1) const {
;         const int g = row >> 11, rowg = row & 2047, j = col >> 4, p = col & 15;
; #pragma unroll
;         for (int i = 0; i < 4; ++i) { v0[i] = gelu_tanh(v0[i]); v1[i] = gelu_tanh(v1[i]); }
;         *(GAS u32x4*)(Y + ((size_t)(rowg * 16 + j) * 512 + g * 16 + p)) = pack8(v0, v1);
	v_fmaak_f32 v158, v60, v158, 0xc0135761
	v_fmaak_f32 v159, v61, v159, 0xc0135761
	v_fmaak_f32 v160, v62, v160, 0xc0135761
	v_fmaak_f32 v161, v63, v161, 0xc0135761
	v_mul_f32_e32 v154, v56, v154
	v_mul_f32_e32 v155, v57, v155
	v_mul_f32_e32 v156, v58, v156
	v_mul_f32_e32 v157, v59, v157
	v_mul_f32_e32 v158, v60, v158
	v_mul_f32_e32 v159, v61, v159
	v_mul_f32_e32 v160, v62, v160
	v_mul_f32_e32 v161, v63, v161
	v_exp_f32_e32 v154, v154
	v_exp_f32_e32 v155, v155
	v_exp_f32_e32 v156, v156
	v_exp_f32_e32 v157, v157
	v_exp_f32_e32 v158, v158
	v_exp_f32_e32 v159, v159
	v_exp_f32_e32 v160, v160
	v_exp_f32_e32 v161, v161
	v_add_f32_e32 v154, 1.0, v154
	v_add_f32_e32 v155, 1.0, v155
	v_add_f32_e32 v156, 1.0, v156
	v_add_f32_e32 v157, 1.0, v157
	v_add_f32_e32 v158, 1.0, v158
	v_add_f32_e32 v159, 1.0, v159
	v_add_f32_e32 v160, 1.0, v160
	v_add_f32_e32 v161, 1.0, v161
	v_rcp_f32_e32 v154, v154
	v_rcp_f32_e32 v155, v155
	v_rcp_f32_e32 v156, v156
	v_rcp_f32_e32 v157, v157
	v_rcp_f32_e32 v158, v158
	v_rcp_f32_e32 v159, v159
	v_rcp_f32_e32 v160, v160
	v_rcp_f32_e32 v161, v161
	v_pk_mul_f32 v[154:155], v[56:57], v[154:155]
	v_pk_mul_f32 v[156:157], v[58:59], v[156:157]
	v_pk_mul_f32 v[158:159], v[60:61], v[158:159]
	v_pk_mul_f32 v[160:161], v[62:63], v[160:161]
	v_cvt_pk_bf16_f32 v56, v158, v159
	v_cvt_pk_bf16_f32 v57, v160, v161
	v_cvt_pk_bf16_f32 v58, v154, v155
	v_cvt_pk_bf16_f32 v59, v156, v157
	global_store_dwordx4 v162, v[56:59], s[50:51]
	v_mul_f32_e32 v154, 0xbdd2d3e8, v48
	v_mul_f32_e32 v155, 0xbdd2d3e8, v49
	v_mul_f32_e32 v156, 0xbdd2d3e8, v50
	v_mul_f32_e32 v157, 0xbdd2d3e8, v51
	v_mul_f32_e32 v158, 0xbdd2d3e8, v52
	v_mul_f32_e32 v159, 0xbdd2d3e8, v53
	v_mul_f32_e32 v160, 0xbdd2d3e8, v54
	v_mul_f32_e32 v161, 0xbdd2d3e8, v55
	v_fmaak_f32 v154, v48, v154, 0xc0135761
	v_fmaak_f32 v155, v49, v155, 0xc0135761
	v_fmaak_f32 v156, v50, v156, 0xc0135761
	v_fmaak_f32 v157, v51, v157, 0xc0135761
	v_fmaak_f32 v158, v52, v158, 0xc0135761
	v_fmaak_f32 v159, v53, v159, 0xc0135761
	v_fmaak_f32 v160, v54, v160, 0xc0135761
	v_fmaak_f32 v161, v55, v161, 0xc0135761
	v_mul_f32_e32 v154, v48, v154
	v_mul_f32_e32 v155, v49, v155
	v_mul_f32_e32 v156, v50, v156
	v_mul_f32_e32 v157, v51, v157
	v_mul_f32_e32 v158, v52, v158
	v_mul_f32_e32 v159, v53, v159
	v_mul_f32_e32 v160, v54, v160
	v_mul_f32_e32 v161, v55, v161
	v_exp_f32_e32 v154, v154
	v_exp_f32_e32 v155, v155
	v_exp_f32_e32 v156, v156
	v_exp_f32_e32 v157, v157
	v_exp_f32_e32 v158, v158
	v_exp_f32_e32 v159, v159
	v_exp_f32_e32 v160, v160
	v_exp_f32_e32 v161, v161
	v_add_f32_e32 v154, 1.0, v154
	v_add_f32_e32 v155, 1.0, v155
	v_add_f32_e32 v156, 1.0, v156
	v_add_f32_e32 v157, 1.0, v157
	v_add_f32_e32 v158, 1.0, v158
	v_add_f32_e32 v159, 1.0, v159
	v_add_f32_e32 v160, 1.0, v160
	v_add_f32_e32 v161, 1.0, v161
	v_rcp_f32_e32 v154, v154
	v_rcp_f32_e32 v155, v155
	v_rcp_f32_e32 v156, v156
	v_rcp_f32_e32 v157, v157
	v_rcp_f32_e32 v158, v158
	v_rcp_f32_e32 v159, v159
	v_rcp_f32_e32 v160, v160
	v_rcp_f32_e32 v161, v161
	v_pk_mul_f32 v[154:155], v[48:49], v[154:155]
	v_pk_mul_f32 v[156:157], v[50:51], v[156:157]
	v_pk_mul_f32 v[158:159], v[52:53], v[158:159]
	v_pk_mul_f32 v[160:161], v[54:55], v[160:161]
	v_cvt_pk_bf16_f32 v48, v158, v159
	v_cvt_pk_bf16_f32 v49, v160, v161
	v_cvt_pk_bf16_f32 v50, v154, v155
	v_cvt_pk_bf16_f32 v51, v156, v157
	global_store_dwordx4 v153, v[48:51], s[50:51]
	s_add_u32 s50, s50, 0x40000
	s_addc_u32 s51, s51, 0
	v_mul_f32_e32 v154, 0xbdd2d3e8, v40
	v_mul_f32_e32 v155, 0xbdd2d3e8, v41
	v_mul_f32_e32 v156, 0xbdd2d3e8, v42
	v_mul_f32_e32 v157, 0xbdd2d3e8, v43
	v_mul_f32_e32 v158, 0xbdd2d3e8, v44
	v_mul_f32_e32 v159, 0xbdd2d3e8, v45
	v_mul_f32_e32 v160, 0xbdd2d3e8, v46
	v_mul_f32_e32 v161, 0xbdd2d3e8, v47
	v_fmaak_f32 v154, v40, v154, 0xc0135761
	v_fmaak_f32 v155, v41, v155, 0xc0135761
	v_fmaak_f32 v156, v42, v156, 0xc0135761
	v_fmaak_f32 v157, v43, v157, 0xc0135761
	v_fmaak_f32 v158, v44, v158, 0xc0135761
	v_fmaak_f32 v159, v45, v159, 0xc0135761
	v_fmaak_f32 v160, v46, v160, 0xc0135761
	v_fmaak_f32 v161, v47, v161, 0xc0135761
	v_mul_f32_e32 v154, v40, v154
	v_mul_f32_e32 v155, v41, v155
	v_mul_f32_e32 v156, v42, v156
	v_mul_f32_e32 v157, v43, v157
	v_mul_f32_e32 v158, v44, v158
	v_mul_f32_e32 v159, v45, v159
	v_mul_f32_e32 v160, v46, v160
	v_mul_f32_e32 v161, v47, v161
	v_exp_f32_e32 v154, v154
	v_exp_f32_e32 v155, v155
	v_exp_f32_e32 v156, v156
	v_exp_f32_e32 v157, v157
	v_exp_f32_e32 v158, v158
	v_exp_f32_e32 v159, v159
	v_exp_f32_e32 v160, v160
	v_exp_f32_e32 v161, v161
	v_add_f32_e32 v154, 1.0, v154
	v_add_f32_e32 v155, 1.0, v155
	v_add_f32_e32 v156, 1.0, v156
	v_add_f32_e32 v157, 1.0, v157
	v_add_f32_e32 v158, 1.0, v158
	v_add_f32_e32 v159, 1.0, v159
	v_add_f32_e32 v160, 1.0, v160
	v_add_f32_e32 v161, 1.0, v161
	v_rcp_f32_e32 v154, v154
	v_rcp_f32_e32 v155, v155
	v_rcp_f32_e32 v156, v156
	v_rcp_f32_e32 v157, v157
	v_rcp_f32_e32 v158, v158
	v_rcp_f32_e32 v159, v159
	v_rcp_f32_e32 v160, v160
	v_rcp_f32_e32 v161, v161
	v_pk_mul_f32 v[154:155], v[40:41], v[154:155]
	v_pk_mul_f32 v[156:157], v[42:43], v[156:157]
	v_pk_mul_f32 v[158:159], v[44:45], v[158:159]
	v_pk_mul_f32 v[160:161], v[46:47], v[160:161]
	v_cvt_pk_bf16_f32 v40, v158, v159
	v_cvt_pk_bf16_f32 v41, v160, v161
	v_cvt_pk_bf16_f32 v42, v154, v155
	v_cvt_pk_bf16_f32 v43, v156, v157
	global_store_dwordx4 v162, v[40:43], s[50:51]
	v_mul_f32_e32 v154, 0xbdd2d3e8, v32
	v_mul_f32_e32 v155, 0xbdd2d3e8, v33
	v_mul_f32_e32 v156, 0xbdd2d3e8, v34
	v_mul_f32_e32 v157, 0xbdd2d3e8, v35
	v_mul_f32_e32 v158, 0xbdd2d3e8, v36
	v_mul_f32_e32 v159, 0xbdd2d3e8, v37
	v_mul_f32_e32 v160, 0xbdd2d3e8, v38
	v_mul_f32_e32 v161, 0xbdd2d3e8, v39
; #define GAS __attribute__((address_space(1)))
; __device__ __forceinline__ float fexp2(float x) { return __builtin_amdgcn_exp2f(x); }
; __device__ __forceinline__ float frcp(float x) { return __builtin_amdgcn_rcpf(x); }
; __device__ __forceinline__ float gelu_tanh(float x) { const float u = 0.7978845608028654f * (x + 0.044715f * x * x * x); return x * sigmoidf_(2.f * u); }
; __device__ __forceinline__ u32x4 pack8(f32x4 a, f32x4 b) { u32x4 w; w.x = pk2(a[0], a[1]); w.y = pk2(a[2], a[3]); w.z = pk2(b[0], b[1]); w.w = pk2(b[2], b[3]); return w; }
; __device__ __forceinline__ float sigmoidf_(float x) { return frcp(1.f + fexp2(-x * LOG2E)); }
; __device__ __forceinline__ float siluf_(float x) { return x * sigmoidf_(x); }
;     __device__ __forceinline__ void operator()(const Unit& u, int row, int col, f32x4 v0, f32x4 v1) const {
;         const int g = row >> 11, rowg = row & 2047, j = col >> 4, p = col & 15;
; #pragma unroll
;         for (int i = 0; i < 4; ++i) { v0[i] = gelu_tanh(v0[i]); v1[i] = gelu_tanh(v1[i]); }
;         *(GAS u32x4*)(Y + ((size_t)(rowg * 16 + j) * 512 + g * 16 + p)) = pack8(v0, v1);
	v_fmaak_f32 v154, v32, v154, 0xc0135761
	v_fmaak_f32 v155, v33, v155, 0xc0135761
	v_fmaak_f32 v156, v34, v156, 0xc0135761
	v_fmaak_f32 v157, v35, v157, 0xc0135761
	v_fmaak_f32 v158, v36, v158, 0xc0135761
	v_fmaak_f32 v159, v37, v159, 0xc0135761
	v_fmaak_f32 v160, v38, v160, 0xc0135761
	v_fmaak_f32 v161, v39, v161, 0xc0135761
	v_mul_f32_e32 v154, v32, v154
	v_mul_f32_e32 v155, v33, v155
	v_mul_f32_e32 v156, v34, v156
	v_mul_f32_e32 v157, v35, v157
	v_mul_f32_e32 v158, v36, v158
	v_mul_f32_e32 v159, v37, v159
	v_mul_f32_e32 v160, v38, v160
	v_mul_f32_e32 v161, v39, v161
	v_exp_f32_e32 v154, v154
	v_exp_f32_e32 v155, v155
	v_exp_f32_e32 v156, v156
	v_exp_f32_e32 v157, v157
	v_exp_f32_e32 v158, v158
	v_exp_f32_e32 v159, v159
	v_exp_f32_e32 v160, v160
	v_exp_f32_e32 v161, v161
	v_add_f32_e32 v154, 1.0, v154
	v_add_f32_e32 v155, 1.0, v155
	v_add_f32_e32 v156, 1.0, v156
	v_add_f32_e32 v157, 1.0, v157
	v_add_f32_e32 v158, 1.0, v158
	v_add_f32_e32 v159, 1.0, v159
	v_add_f32_e32 v160, 1.0, v160
	v_add_f32_e32 v161, 1.0, v161
	v_rcp_f32_e32 v154, v154
	v_rcp_f32_e32 v155, v155
	v_rcp_f32_e32 v156, v156
	v_rcp_f32_e32 v157, v157
	v_rcp_f32_e32 v158, v158
	v_rcp_f32_e32 v159, v159
	v_rcp_f32_e32 v160, v160
	v_rcp_f32_e32 v161, v161
	v_pk_mul_f32 v[154:155], v[32:33], v[154:155]
	v_pk_mul_f32 v[156:157], v[34:35], v[156:157]
	v_pk_mul_f32 v[158:159], v[36:37], v[158:159]
	v_pk_mul_f32 v[160:161], v[38:39], v[160:161]
	v_cvt_pk_bf16_f32 v32, v158, v159
	v_cvt_pk_bf16_f32 v33, v160, v161
	v_cvt_pk_bf16_f32 v34, v154, v155
	v_cvt_pk_bf16_f32 v35, v156, v157
	global_store_dwordx4 v153, v[32:35], s[50:51]
	s_add_u32 s50, s50, 0x40000
	s_addc_u32 s51, s51, 0
	v_mul_f32_e32 v154, 0xbdd2d3e8, v24
	v_mul_f32_e32 v155, 0xbdd2d3e8, v25
	v_mul_f32_e32 v156, 0xbdd2d3e8, v26
	v_mul_f32_e32 v157, 0xbdd2d3e8, v27
	v_mul_f32_e32 v158, 0xbdd2d3e8, v28
	v_mul_f32_e32 v159, 0xbdd2d3e8, v29
	v_mul_f32_e32 v160, 0xbdd2d3e8, v30
	v_mul_f32_e32 v161, 0xbdd2d3e8, v31
	v_fmaak_f32 v154, v24, v154, 0xc0135761
	v_fmaak_f32 v155, v25, v155, 0xc0135761
	v_fmaak_f32 v156, v26, v156, 0xc0135761
	v_fmaak_f32 v157, v27, v157, 0xc0135761
	v_fmaak_f32 v158, v28, v158, 0xc0135761
	v_fmaak_f32 v159, v29, v159, 0xc0135761
	v_fmaak_f32 v160, v30, v160, 0xc0135761
	v_fmaak_f32 v161, v31, v161, 0xc0135761
	v_mul_f32_e32 v154, v24, v154
	v_mul_f32_e32 v155, v25, v155
	v_mul_f32_e32 v156, v26, v156
	v_mul_f32_e32 v157, v27, v157
	v_mul_f32_e32 v158, v28, v158
	v_mul_f32_e32 v159, v29, v159
	v_mul_f32_e32 v160, v30, v160
	v_mul_f32_e32 v161, v31, v161
	v_exp_f32_e32 v154, v154
	v_exp_f32_e32 v155, v155
	v_exp_f32_e32 v156, v156
	v_exp_f32_e32 v157, v157
	v_exp_f32_e32 v158, v158
	v_exp_f32_e32 v159, v159
	v_exp_f32_e32 v160, v160
	v_exp_f32_e32 v161, v161
	v_add_f32_e32 v154, 1.0, v154
	v_add_f32_e32 v155, 1.0, v155
	v_add_f32_e32 v156, 1.0, v156
	v_add_f32_e32 v157, 1.0, v157
	v_add_f32_e32 v158, 1.0, v158
	v_add_f32_e32 v159, 1.0, v159
	v_add_f32_e32 v160, 1.0, v160
	v_add_f32_e32 v161, 1.0, v161
	v_rcp_f32_e32 v154, v154
	v_rcp_f32_e32 v155, v155
	v_rcp_f32_e32 v156, v156
	v_rcp_f32_e32 v157, v157
	v_rcp_f32_e32 v158, v158
	v_rcp_f32_e32 v159, v159
	v_rcp_f32_e32 v160, v160
	v_rcp_f32_e32 v161, v161
	v_pk_mul_f32 v[154:155], v[24:25], v[154:155]
	v_pk_mul_f32 v[156:157], v[26:27], v[156:157]
	v_pk_mul_f32 v[158:159], v[28:29], v[158:159]
	v_pk_mul_f32 v[160:161], v[30:31], v[160:161]
	v_cvt_pk_bf16_f32 v24, v158, v159
	v_cvt_pk_bf16_f32 v25, v160, v161
	v_cvt_pk_bf16_f32 v26, v154, v155
	v_cvt_pk_bf16_f32 v27, v156, v157
	global_store_dwordx4 v162, v[24:27], s[50:51]
	v_mul_f32_e32 v154, 0xbdd2d3e8, v16
	v_mul_f32_e32 v155, 0xbdd2d3e8, v17
	v_mul_f32_e32 v156, 0xbdd2d3e8, v18
	v_mul_f32_e32 v157, 0xbdd2d3e8, v19
	v_mul_f32_e32 v158, 0xbdd2d3e8, v20
	v_mul_f32_e32 v159, 0xbdd2d3e8, v21
	v_mul_f32_e32 v160, 0xbdd2d3e8, v22
	v_mul_f32_e32 v161, 0xbdd2d3e8, v23
	v_fmaak_f32 v154, v16, v154, 0xc0135761
	v_fmaak_f32 v155, v17, v155, 0xc0135761
	v_fmaak_f32 v156, v18, v156, 0xc0135761
	v_fmaak_f32 v157, v19, v157, 0xc0135761
	v_fmaak_f32 v158, v20, v158, 0xc0135761
	v_fmaak_f32 v159, v21, v159, 0xc0135761
	v_fmaak_f32 v160, v22, v160, 0xc0135761
	v_fmaak_f32 v161, v23, v161, 0xc0135761
	v_mul_f32_e32 v154, v16, v154
	v_mul_f32_e32 v155, v17, v155
	v_mul_f32_e32 v156, v18, v156
	v_mul_f32_e32 v157, v19, v157
	v_mul_f32_e32 v158, v20, v158
	v_mul_f32_e32 v159, v21, v159
	v_mul_f32_e32 v160, v22, v160
	v_mul_f32_e32 v161, v23, v161
	v_exp_f32_e32 v154, v154
	v_exp_f32_e32 v155, v155
	v_exp_f32_e32 v156, v156
	v_exp_f32_e32 v157, v157
	v_exp_f32_e32 v158, v158
	v_exp_f32_e32 v159, v159
	v_exp_f32_e32 v160, v160
	v_exp_f32_e32 v161, v161
	v_add_f32_e32 v154, 1.0, v154
	v_add_f32_e32 v155, 1.0, v155
	v_add_f32_e32 v156, 1.0, v156
; #define GAS __attribute__((address_space(1)))
; __device__ __forceinline__ float fexp2(float x) { return __builtin_amdgcn_exp2f(x); }
; __device__ __forceinline__ float frcp(float x) { return __builtin_amdgcn_rcpf(x); }
; __device__ __forceinline__ float gelu_tanh(float x) { const float u = 0.7978845608028654f * (x + 0.044715f * x * x * x); return x * sigmoidf_(2.f * u); }
; __device__ __forceinline__ u32x4 pack8(f32x4 a, f32x4 b) { u32x4 w; w.x = pk2(a[0], a[1]); w.y = pk2(a[2], a[3]); w.z = pk2(b[0], b[1]); w.w = pk2(b[2], b[3]); return w; }
; __device__ __forceinline__ float sigmoidf_(float x) { return frcp(1.f + fexp2(-x * LOG2E)); }
; __device__ __forceinline__ float siluf_(float x) { return x * sigmoidf_(x); }
;     __device__ __forceinline__ void operator()(const Unit& u, int row, int col, f32x4 v0, f32x4 v1) const {
;         const int g = row >> 11, rowg = row & 2047, j = col >> 4, p = col & 15;
; #pragma unroll
;         for (int i = 0; i < 4; ++i) { v0[i] = gelu_tanh(v0[i]); v1[i] = gelu_tanh(v1[i]); }
;         *(GAS u32x4*)(Y + ((size_t)(rowg * 16 + j) * 512 + g * 16 + p)) = pack8(v0, v1);
	v_add_f32_e32 v157, 1.0, v157
	v_add_f32_e32 v158, 1.0, v158
	v_add_f32_e32 v159, 1.0, v159
	v_add_f32_e32 v160, 1.0, v160
	v_add_f32_e32 v161, 1.0, v161
	v_rcp_f32_e32 v154, v154
	v_rcp_f32_e32 v155, v155
	v_rcp_f32_e32 v156, v156
	v_rcp_f32_e32 v157, v157
	v_rcp_f32_e32 v158, v158
	v_rcp_f32_e32 v159, v159
	v_rcp_f32_e32 v160, v160
	v_rcp_f32_e32 v161, v161
	v_pk_mul_f32 v[154:155], v[16:17], v[154:155]
	v_pk_mul_f32 v[156:157], v[18:19], v[156:157]
	v_pk_mul_f32 v[158:159], v[20:21], v[158:159]
	v_pk_mul_f32 v[160:161], v[22:23], v[160:161]
	v_cvt_pk_bf16_f32 v16, v158, v159
	v_cvt_pk_bf16_f32 v17, v160, v161
	v_cvt_pk_bf16_f32 v18, v154, v155
	v_cvt_pk_bf16_f32 v19, v156, v157
	global_store_dwordx4 v153, v[16:19], s[50:51]
	s_add_u32 s50, s50, 0x40000
	s_addc_u32 s51, s51, 0
	v_mul_f32_e32 v154, 0xbdd2d3e8, v8
	v_mul_f32_e32 v155, 0xbdd2d3e8, v9
	v_mul_f32_e32 v156, 0xbdd2d3e8, v10
	v_mul_f32_e32 v157, 0xbdd2d3e8, v11
	v_mul_f32_e32 v158, 0xbdd2d3e8, v12
	v_mul_f32_e32 v159, 0xbdd2d3e8, v13
	v_mul_f32_e32 v160, 0xbdd2d3e8, v14
	v_mul_f32_e32 v161, 0xbdd2d3e8, v15
	v_fmaak_f32 v154, v8, v154, 0xc0135761
	v_fmaak_f32 v155, v9, v155, 0xc0135761
	v_fmaak_f32 v156, v10, v156, 0xc0135761
	v_fmaak_f32 v157, v11, v157, 0xc0135761
	v_fmaak_f32 v158, v12, v158, 0xc0135761
	v_fmaak_f32 v159, v13, v159, 0xc0135761
	v_fmaak_f32 v160, v14, v160, 0xc0135761
	v_fmaak_f32 v161, v15, v161, 0xc0135761
	v_mul_f32_e32 v154, v8, v154
	v_mul_f32_e32 v155, v9, v155
	v_mul_f32_e32 v156, v10, v156
	v_mul_f32_e32 v157, v11, v157
	v_mul_f32_e32 v158, v12, v158
	v_mul_f32_e32 v159, v13, v159
	v_mul_f32_e32 v160, v14, v160
	v_mul_f32_e32 v161, v15, v161
	v_exp_f32_e32 v154, v154
	v_exp_f32_e32 v155, v155
	v_exp_f32_e32 v156, v156
	v_exp_f32_e32 v157, v157
	v_exp_f32_e32 v158, v158
	v_exp_f32_e32 v159, v159
	v_exp_f32_e32 v160, v160
	v_exp_f32_e32 v161, v161
	v_add_f32_e32 v154, 1.0, v154
	v_add_f32_e32 v155, 1.0, v155
	v_add_f32_e32 v156, 1.0, v156
	v_add_f32_e32 v157, 1.0, v157
	v_add_f32_e32 v158, 1.0, v158
	v_add_f32_e32 v159, 1.0, v159
	v_add_f32_e32 v160, 1.0, v160
	v_add_f32_e32 v161, 1.0, v161
	v_rcp_f32_e32 v154, v154
	v_rcp_f32_e32 v155, v155
	v_rcp_f32_e32 v156, v156
	v_rcp_f32_e32 v157, v157
	v_rcp_f32_e32 v158, v158
	v_rcp_f32_e32 v159, v159
	v_rcp_f32_e32 v160, v160
	v_rcp_f32_e32 v161, v161
	v_pk_mul_f32 v[154:155], v[8:9], v[154:155]
	v_pk_mul_f32 v[156:157], v[10:11], v[156:157]
	v_pk_mul_f32 v[158:159], v[12:13], v[158:159]
	v_pk_mul_f32 v[160:161], v[14:15], v[160:161]
	v_cvt_pk_bf16_f32 v8, v158, v159
	v_cvt_pk_bf16_f32 v9, v160, v161
	v_cvt_pk_bf16_f32 v10, v154, v155
	v_cvt_pk_bf16_f32 v11, v156, v157
	global_store_dwordx4 v162, v[8:11], s[50:51]
	v_mul_f32_e32 v154, 0xbdd2d3e8, v0
	v_mul_f32_e32 v155, 0xbdd2d3e8, v1
	v_mul_f32_e32 v156, 0xbdd2d3e8, v2
	v_mul_f32_e32 v157, 0xbdd2d3e8, v3
	v_mul_f32_e32 v158, 0xbdd2d3e8, v4
	v_mul_f32_e32 v159, 0xbdd2d3e8, v5
	v_mul_f32_e32 v160, 0xbdd2d3e8, v6
	v_mul_f32_e32 v161, 0xbdd2d3e8, v7
	v_fmaak_f32 v154, v0, v154, 0xc0135761
	v_fmaak_f32 v155, v1, v155, 0xc0135761
	v_fmaak_f32 v156, v2, v156, 0xc0135761
	v_fmaak_f32 v157, v3, v157, 0xc0135761
	v_fmaak_f32 v158, v4, v158, 0xc0135761
	v_fmaak_f32 v159, v5, v159, 0xc0135761
	v_fmaak_f32 v160, v6, v160, 0xc0135761
	v_fmaak_f32 v161, v7, v161, 0xc0135761
	v_mul_f32_e32 v154, v0, v154
	v_mul_f32_e32 v155, v1, v155
	v_mul_f32_e32 v156, v2, v156
	v_mul_f32_e32 v157, v3, v157
	v_mul_f32_e32 v158, v4, v158
	v_mul_f32_e32 v159, v5, v159
	v_mul_f32_e32 v160, v6, v160
	v_mul_f32_e32 v161, v7, v161
	v_exp_f32_e32 v154, v154
	v_exp_f32_e32 v155, v155
	v_exp_f32_e32 v156, v156
	v_exp_f32_e32 v157, v157
	v_exp_f32_e32 v158, v158
	v_exp_f32_e32 v159, v159
	v_exp_f32_e32 v160, v160
	v_exp_f32_e32 v161, v161
	v_add_f32_e32 v154, 1.0, v154
	v_add_f32_e32 v155, 1.0, v155
	v_add_f32_e32 v156, 1.0, v156
	v_add_f32_e32 v157, 1.0, v157
	v_add_f32_e32 v158, 1.0, v158
	v_add_f32_e32 v159, 1.0, v159
	v_add_f32_e32 v160, 1.0, v160
	v_add_f32_e32 v161, 1.0, v161
	v_rcp_f32_e32 v154, v154
	v_rcp_f32_e32 v155, v155
	v_rcp_f32_e32 v156, v156
	v_rcp_f32_e32 v157, v157
	v_rcp_f32_e32 v158, v158
	v_rcp_f32_e32 v159, v159
	v_rcp_f32_e32 v160, v160
	v_rcp_f32_e32 v161, v161
	v_pk_mul_f32 v[154:155], v[0:1], v[154:155]
	v_pk_mul_f32 v[156:157], v[2:3], v[156:157]
	v_pk_mul_f32 v[158:159], v[4:5], v[158:159]
	v_pk_mul_f32 v[160:161], v[6:7], v[160:161]
	v_cvt_pk_bf16_f32 v0, v158, v159
	v_cvt_pk_bf16_f32 v1, v160, v161
	v_cvt_pk_bf16_f32 v2, v154, v155
	v_cvt_pk_bf16_f32 v3, v156, v157
	global_store_dwordx4 v153, v[0:3], s[50:51]
	s_andn2_b64 vcc, exec, s[8:9]
	s_mov_b64 s[8:9], -1
	s_cbranch_vccnz .LBB0_691
	s_andn2_b64 vcc, exec, s[34:35]
	s_cbranch_vccnz .LBB0_690
	s_barrier
	s_branch .LBB0_690
